# attn0 prompt part: K tiles fragment-major too (all k rows of layer 0)
# speedup vs baseline: 1.0061x; 1.0022x over previous
.LBB0_590:
	s_movk_i32 s0, 0x1ff
	v_cmp_lt_i32_e32 vcc, s0, v1
	v_lshlrev_b32_e32 v2, 1, v156
	v_lshl_or_b32 v2, v154, 5, v2
	s_and_saveexec_b64 s[0:1], vcc
	s_xor_b64 s[0:1], exec, s[0:1]
	s_cbranch_execz .LBB0_610
	v_lshlrev_b32_e32 v4, 3, v1
	v_and_b32_e32 v4, 0x7fffff00, v4
	v_bfe_u32 v183, v1, 1, 4
	v_add_u32_e32 v16, 0xfffff000, v4
	v_lshlrev_b32_e32 v4, 7, v1
	v_and_b32_e32 v4, 0x80, v4
	v_lshlrev_b32_e32 v6, 13, v183
	v_or3_b32 v186, v4, v155, v16
	v_add_u32_e32 v4, v6, v16
	v_mov_b32_e32 v5, v3
	v_lshlrev_b64 v[4:5], 7, v[4:5]
	v_lshl_add_u64 v[192:193], s[38:39], 0, v[4:5]
	v_lshl_add_u64 v[18:19], v[192:193], 0, v[2:3]
	v_add_u32_e32 v8, v6, v186
	global_load_dwordx4 v[4:7], v[18:19], off
	v_mov_b32_e32 v9, v3
	v_lshlrev_b64 v[8:9], 7, v[8:9]
	v_lshl_add_u64 v[20:21], v[152:153], 0, v[8:9]
	global_load_dwordx4 v[82:85], v[20:21], off
	global_load_dwordx4 v[8:11], v[18:19], off offset:1024
	global_load_dwordx4 v[74:77], v[20:21], off offset:32
	global_load_dwordx4 v[12:15], v[18:19], off offset:2048
	global_load_dwordx4 v[70:73], v[20:21], off offset:64
	v_mov_b32_e32 v23, v3
	v_lshlrev_b32_e32 v22, 20, v183
	v_mov_b32_e32 v17, v3
	v_lshl_add_u64 v[22:23], s[54:55], 0, v[22:23]
	v_mov_b32_e32 v177, v3
	v_lshl_add_u64 v[202:203], v[16:17], 1, v[22:23]
	v_lshl_add_u64 v[200:201], v[202:203], 0, v[176:177]
	global_load_dwordx4 v[16:19], v[18:19], off offset:3072
	s_nop 0
	global_load_dwordx4 v[110:113], v[200:201], off
	global_load_dwordx4 v[54:57], v[200:201], off offset:32
	global_load_dwordx4 v[78:81], v[20:21], off offset:96
	v_mov_b32_e32 v38, v36
	v_mov_b32_e32 v39, v36
	v_mov_b32_e32 v40, v36
	v_mov_b32_e32 v41, v36
	v_mov_b32_e32 v42, v36
	v_mov_b32_e32 v43, v36
	v_mov_b32_e32 v44, v36
	v_mov_b32_e32 v45, v36
	v_mov_b32_e32 v46, v36
	v_mov_b32_e32 v47, v36
	v_mov_b32_e32 v48, v36
	v_mov_b32_e32 v49, v36
	v_mov_b32_e32 v50, v36
	v_mov_b32_e32 v51, v36
	v_mov_b32_e32 v37, v36
	v_mov_b64_e32 v[52:53], v[50:51]
	v_mov_b64_e32 v[50:51], v[48:49]
	v_mov_b64_e32 v[48:49], v[46:47]
	v_mov_b64_e32 v[46:47], v[44:45]
	v_mov_b64_e32 v[44:45], v[42:43]
	v_mov_b64_e32 v[42:43], v[40:41]
	v_mov_b64_e32 v[40:41], v[38:39]
	v_mov_b64_e32 v[38:39], v[36:37]
	v_lshlrev_b32_e32 v190, 1, v170
	v_mov_b32_e32 v191, v3
	s_mov_b64 s[4:5], 0x1000
	v_lshlrev_b32_e32 v188, 1, v172
	v_mov_b32_e32 v189, v3
	v_lshl_add_u64 v[22:23], v[202:203], 0, v[190:191]
	v_lshl_add_u64 v[20:21], v[192:193], 0, s[4:5]
	v_add_u32_e32 v198, 0x400, v2
	v_mov_b32_e32 v199, v3
	v_add_u32_e32 v196, 0x800, v2
	v_mov_b32_e32 v197, v3
	v_add_u32_e32 v194, 0xc00, v2
	v_mov_b32_e32 v195, v3
	v_lshl_add_u64 v[24:25], v[202:203], 0, v[188:189]
	global_load_dwordx4 v[106:109], v[22:23], off
	global_load_dwordx4 v[58:61], v[24:25], off
	v_lshl_add_u64 v[22:23], v[20:21], 0, v[2:3]
	v_lshl_add_u64 v[26:27], v[202:203], 0, 64
	global_load_dwordx4 v[98:101], v[200:201], off offset:64
	global_load_dwordx4 v[62:65], v[200:201], off offset:96
	s_waitcnt vmcnt(0)
	v_mfma_f32_32x32x16_bf16 v[38:53], v[4:7], v[82:85], v[38:53]
	v_lshl_add_u64 v[4:5], v[26:27], 0, v[190:191]
	v_lshl_add_u64 v[6:7], v[26:27], 0, v[188:189]
	v_mfma_f32_32x32x16_bf16 v[38:53], v[8:11], v[74:77], v[38:53]
	v_lshl_add_u64 v[8:9], v[20:21], 0, v[198:199]
	v_lshl_add_u64 v[10:11], v[20:21], 0, v[196:197]
	v_lshl_add_u64 v[20:21], v[20:21], 0, v[194:195]
	global_load_dwordx4 v[102:105], v[22:23], off
	global_load_dwordx4 v[94:97], v[8:9], off
	global_load_dwordx4 v[86:89], v[10:11], off
	global_load_dwordx4 v[114:117], v[20:21], off
	global_load_dwordx4 v[90:93], v[4:5], off
	global_load_dwordx4 v[66:69], v[6:7], off
	v_mfma_f32_32x32x16_bf16 v[38:53], v[12:15], v[70:73], v[38:53]
	v_mfma_f32_32x32x16_bf16 v[38:53], v[16:19], v[78:81], v[38:53]
	s_nop 11
	v_max3_f32 v4, v38, s69, v39
	v_max3_f32 v4, v4, v40, v41
	v_max3_f32 v4, v4, v42, v43
	v_max3_f32 v4, v4, v44, v45
	v_max3_f32 v4, v4, v46, v47
	v_max3_f32 v4, v4, v48, v49
	v_max3_f32 v4, v4, v50, v51
	v_max3_f32 v4, v4, v52, v53
	v_cmp_lt_f32_e32 vcc, s22, v4
	s_cbranch_vccz .LBB0_593
	v_mbcnt_hi_u32_b32 v5, -1, v222
	v_and_b32_e32 v7, 64, v5
	v_xor_b32_e32 v6, 32, v5
	v_add_u32_e32 v7, 64, v7
	v_cmp_lt_i32_e32 vcc, v6, v7
	s_nop 1
	v_cndmask_b32_e32 v5, v5, v6, vcc
	v_lshlrev_b32_e32 v5, 2, v5
	ds_bpermute_b32 v5, v5, v4
	s_waitcnt lgkmcnt(0)
	v_max3_f32 v6, v4, v5, 0
	v_exp_f32_e64 v4, -v6
	v_add_f32_e32 v37, 0, v6
	v_pk_add_f32 v[38:39], v[38:39], v[6:7] op_sel_hi:[1,0] neg_lo:[0,1] neg_hi:[0,1]
	v_pk_add_f32 v[40:41], v[40:41], v[6:7] op_sel_hi:[1,0] neg_lo:[0,1] neg_hi:[0,1]
	v_pk_add_f32 v[42:43], v[42:43], v[6:7] op_sel_hi:[1,0] neg_lo:[0,1] neg_hi:[0,1]
	v_pk_add_f32 v[44:45], v[44:45], v[6:7] op_sel_hi:[1,0] neg_lo:[0,1] neg_hi:[0,1]
	v_mul_f32_e32 v4, 0, v4
	v_pk_add_f32 v[46:47], v[46:47], v[6:7] op_sel_hi:[1,0] neg_lo:[0,1] neg_hi:[0,1]
	v_pk_add_f32 v[48:49], v[48:49], v[6:7] op_sel_hi:[1,0] neg_lo:[0,1] neg_hi:[0,1]
	v_pk_add_f32 v[50:51], v[50:51], v[6:7] op_sel_hi:[1,0] neg_lo:[0,1] neg_hi:[0,1]
	v_pk_add_f32 v[52:53], v[52:53], v[6:7] op_sel_hi:[1,0] neg_lo:[0,1] neg_hi:[0,1]
	s_branch .LBB0_594

.Lp0_loop:
	v_mov_b32_e32 v112, v1
	v_mov_b32_e32 v113, v15
	v_ashrrev_i32_e32 v2, 10, v1
	v_bfe_u32 v17, v1, 7, 13
	v_mov_b64_e32 v[4:5], s[34:35]
	v_and_b32_e32 v6, 0xfffffc00, v2
	v_bfe_u32 v16, v1, 3, 4
	v_mad_u64_u32 v[4:5], s[0:1], v17, s67, v[4:5]
	v_ashrrev_i32_e32 v7, 31, v6
	v_lshl_add_u64 v[4:5], v[6:7], 1, v[4:5]
	v_lshlrev_b32_e32 v2, 7, v16
	v_lshl_add_u64 v[4:5], v[4:5], 0, v[2:3]
	v_and_b32_e32 v2, 56, v15
	v_mov_b32_e32 v23, v3
	v_lshlrev_b32_e32 v22, 1, v2
	v_lshl_add_u64 v[4:5], v[4:5], 0, v[22:23]
	global_load_dwordx4 v[96:99], v[4:5], off
	v_add_u32_e32 v1, s2, v1
	v_add_u32_e32 v15, s3, v15
	v_ashrrev_i32_e32 v2, 10, v1
	v_bfe_u32 v17, v1, 7, 13
	v_mov_b64_e32 v[4:5], s[34:35]
	v_and_b32_e32 v6, 0xfffffc00, v2
	v_bfe_u32 v16, v1, 3, 4
	v_mad_u64_u32 v[4:5], s[0:1], v17, s67, v[4:5]
	v_ashrrev_i32_e32 v7, 31, v6
	v_lshl_add_u64 v[4:5], v[6:7], 1, v[4:5]
	v_lshlrev_b32_e32 v2, 7, v16
	v_lshl_add_u64 v[4:5], v[4:5], 0, v[2:3]
	v_and_b32_e32 v2, 56, v15
	v_mov_b32_e32 v23, v3
	v_lshlrev_b32_e32 v22, 1, v2
	v_lshl_add_u64 v[4:5], v[4:5], 0, v[22:23]
	global_load_dwordx4 v[100:103], v[4:5], off
	v_add_u32_e32 v1, s2, v1
	v_add_u32_e32 v15, s3, v15
	v_ashrrev_i32_e32 v2, 10, v1
	v_bfe_u32 v17, v1, 7, 13
	v_mov_b64_e32 v[4:5], s[34:35]
	v_and_b32_e32 v6, 0xfffffc00, v2
	v_bfe_u32 v16, v1, 3, 4
	v_mad_u64_u32 v[4:5], s[0:1], v17, s67, v[4:5]
	v_ashrrev_i32_e32 v7, 31, v6
	v_lshl_add_u64 v[4:5], v[6:7], 1, v[4:5]
	v_lshlrev_b32_e32 v2, 7, v16
	v_lshl_add_u64 v[4:5], v[4:5], 0, v[2:3]
	v_and_b32_e32 v2, 56, v15
	v_mov_b32_e32 v23, v3
	v_lshlrev_b32_e32 v22, 1, v2
	v_lshl_add_u64 v[4:5], v[4:5], 0, v[22:23]
	global_load_dwordx4 v[104:107], v[4:5], off
	v_add_u32_e32 v1, s2, v1
	v_add_u32_e32 v15, s3, v15
	v_ashrrev_i32_e32 v2, 10, v1
	v_bfe_u32 v17, v1, 7, 13
	v_mov_b64_e32 v[4:5], s[34:35]
	v_and_b32_e32 v6, 0xfffffc00, v2
	v_bfe_u32 v16, v1, 3, 4
	v_mad_u64_u32 v[4:5], s[0:1], v17, s67, v[4:5]
	v_ashrrev_i32_e32 v7, 31, v6
	v_lshl_add_u64 v[4:5], v[6:7], 1, v[4:5]
	v_lshlrev_b32_e32 v2, 7, v16
	v_lshl_add_u64 v[4:5], v[4:5], 0, v[2:3]
	v_and_b32_e32 v2, 56, v15
	v_mov_b32_e32 v23, v3
	v_lshlrev_b32_e32 v22, 1, v2
	v_lshl_add_u64 v[4:5], v[4:5], 0, v[22:23]
	global_load_dwordx4 v[108:111], v[4:5], off
	v_mov_b32_e32 v1, v112
	v_mov_b32_e32 v15, v113
	v_ashrrev_i32_e32 v2, 10, v1
	v_bfe_u32 v17, v1, 7, 13
	v_mov_b64_e32 v[4:5], s[34:35]
	v_and_b32_e32 v6, 0xfffffc00, v2
	v_bfe_u32 v16, v1, 3, 4
	v_mad_u64_u32 v[4:5], s[0:1], v17, s67, v[4:5]
	v_ashrrev_i32_e32 v7, 31, v6
	v_lshl_add_u64 v[4:5], v[6:7], 1, v[4:5]
	v_lshlrev_b32_e32 v2, 7, v16
	v_lshl_add_u64 v[4:5], v[4:5], 0, v[2:3]
	v_cmp_lt_u32_e32 vcc, s15, v1
	v_and_b32_e32 v2, 56, v15
	v_mov_b32_e32 v23, v3
	v_lshlrev_b32_e32 v22, 1, v2
	v_lshl_add_u64 v[4:5], v[4:5], 0, v[22:23]
	s_waitcnt vmcnt(3)
	v_mov_b64_e32 v[4:5], v[96:97]
	v_mov_b64_e32 v[6:7], v[98:99]
	v_lshlrev_b32_e32 v2, 2, v2
	v_mov_b32_e32 v37, 0xe8a0000
	s_movk_i32 s0, 0x1000
	v_cmp_gt_u32_e64 s[0:1], s0, v17
	v_cndmask_b32_e32 v8, v80, v88, vcc
	v_cndmask_b32_e32 v9, v81, v89, vcc
	v_cndmask_b32_e32 v10, v82, v90, vcc
	v_cndmask_b32_e32 v11, v83, v91, vcc
	v_cndmask_b32_e32 v18, v84, v92, vcc
	v_cndmask_b32_e32 v19, v85, v93, vcc
	v_cndmask_b32_e32 v20, v86, v94, vcc
	v_cndmask_b32_e32 v21, v87, v95, vcc
	v_lshlrev_b32_e32 v24, 16, v4
	v_and_b32_e32 v25, 0xffff0000, v4
	v_lshlrev_b32_e32 v4, 16, v5
	v_and_b32_e32 v5, 0xffff0000, v5
	v_pk_mul_f32 v[28:29], v[24:25], v[24:25]
	v_pk_mul_f32 v[30:31], v[4:5], v[4:5]
	v_add_f32_e32 v28, v28, v29
	v_lshlrev_b32_e32 v26, 16, v6
	v_and_b32_e32 v27, 0xffff0000, v6
	v_add_f32_e32 v28, v28, v30
	v_pk_mul_f32 v[32:33], v[26:27], v[26:27]
	v_add_f32_e32 v28, v31, v28
	v_lshlrev_b32_e32 v6, 16, v7
	v_and_b32_e32 v7, 0xffff0000, v7
	v_add_f32_e32 v28, v32, v28
	v_pk_mul_f32 v[34:35], v[6:7], v[6:7]
	v_add_f32_e32 v28, v33, v28
	v_add_f32_e32 v28, v34, v28
	v_add_f32_e32 v28, v35, v28
	ds_bpermute_b32 v30, v12, v28
	v_mov_b32_e32 v29, v3
	v_mov_b32_e32 v31, v3
	v_mov_b32_e32 v33, v3
	v_lshlrev_b32_e32 v32, 7, v17
	s_mov_b64 s[98:99], vcc
	v_and_b32_e32 v120, 31, v17
	v_lshlrev_b32_e32 v120, 5, v120
	v_and_b32_e32 v121, 0xffffffe0, v17
	v_lshl_or_b32 v120, v121, 7, v120
	v_bfe_u32 v121, v15, 4, 2
	v_lshl_or_b32 v120, v121, 10, v120
	v_bfe_u32 v121, v15, 3, 1
	v_lshl_or_b32 v120, v121, 4, v120
	v_cndmask_b32_e64 v32, v32, v120, s[98:99]
	s_waitcnt lgkmcnt(0)
	v_add_f32_e32 v28, v28, v30
	ds_bpermute_b32 v34, v13, v28
	v_lshlrev_b32_e32 v30, 20, v16
	v_cndmask_b32_e64 v17, v232, 1.0, vcc
	s_waitcnt lgkmcnt(0)
	v_add_f32_e32 v34, v28, v34
	ds_bpermute_b32 v35, v14, v34
	v_mov_b32_e32 v28, 0xd8a0000
	v_cndmask_b32_e32 v28, v28, v37, vcc
	v_lshl_add_u64 v[28:29], s[28:29], 0, v[28:29]
	v_lshl_add_u64 v[28:29], v[28:29], 0, v[30:31]
	s_waitcnt lgkmcnt(0)
	v_add_f32_e32 v34, v34, v35
	v_fmamk_f32 v34, v34, 0x3c800000, v218
	v_mul_f32_e32 v35, 0x4b800000, v34
	v_cmp_gt_f32_e64 s[4:5], s71, v34
	v_lshl_add_u64 v[28:29], v[28:29], 0, v[32:33]
	v_cndmask_b32_e64 v22, v22, v3, s[98:99]
	v_lshl_add_u64 v[22:23], v[28:29], 0, v[22:23]
	v_cndmask_b32_e64 v34, v34, v35, s[4:5]
	v_rsq_f32_e32 v34, v34
	s_nop 0
	v_mul_f32_e32 v28, 0x45800000, v34
	v_cndmask_b32_e64 v28, v34, v28, s[4:5]
	v_mul_f32_e32 v28, v17, v28
	s_and_b64 s[4:5], vcc, s[0:1]
	v_pk_mul_f32 v[8:9], v[8:9], v[28:29] op_sel_hi:[1,0]
	v_pk_mul_f32 v[10:11], v[10:11], v[28:29] op_sel_hi:[1,0]
	v_pk_mul_f32 v[18:19], v[18:19], v[28:29] op_sel_hi:[1,0]
	v_pk_mul_f32 v[20:21], v[20:21], v[28:29] op_sel_hi:[1,0]
	v_pk_mul_f32 v[8:9], v[8:9], v[24:25]
	v_pk_mul_f32 v[10:11], v[10:11], v[4:5]
	v_pk_mul_f32 v[4:5], v[18:19], v[26:27]
	v_pk_mul_f32 v[6:7], v[20:21], v[6:7]
	v_cvt_pk_bf16_f32 v18, v8, v9
	v_cvt_pk_bf16_f32 v19, v10, v11
	v_cvt_pk_bf16_f32 v20, v4, v5
	v_cvt_pk_bf16_f32 v21, v6, v7
	global_store_dwordx4 v[22:23], v[18:21], off
	s_and_saveexec_b64 s[0:1], s[4:5]
	s_cbranch_execz .Lp0_t0
	v_lshrrev_b32_e32 v17, 7, v1
	v_lshrrev_b32_e32 v18, 11, v1
	v_and_or_b32 v16, v18, s16, v16
	v_lshlrev_b32_e32 v17, 8, v17
	v_perm_b32 v16, v16, v17, s17
	v_mov_b32_e32 v17, v3
	v_lshl_add_u64 v[16:17], s[8:9], 0, v[16:17]
	v_lshl_add_u64 v[16:17], v[16:17], 0, v[2:3]
	global_store_dwordx4 v[16:17], v[8:11], off
	global_store_dwordx4 v[16:17], v[4:7], off offset:16
.Lp0_t0:
	s_or_b64 exec, exec, s[0:1]
	v_add_u32_e32 v1, s2, v1
	v_add_u32_e32 v15, s3, v15
	v_ashrrev_i32_e32 v2, 10, v1
	v_bfe_u32 v17, v1, 7, 13
	v_mov_b64_e32 v[4:5], s[34:35]
	v_and_b32_e32 v6, 0xfffffc00, v2
	v_bfe_u32 v16, v1, 3, 4
	v_mad_u64_u32 v[4:5], s[0:1], v17, s67, v[4:5]
	v_ashrrev_i32_e32 v7, 31, v6
	v_lshl_add_u64 v[4:5], v[6:7], 1, v[4:5]
	v_lshlrev_b32_e32 v2, 7, v16
	v_lshl_add_u64 v[4:5], v[4:5], 0, v[2:3]
	v_cmp_lt_u32_e32 vcc, s15, v1
	v_and_b32_e32 v2, 56, v15
	v_mov_b32_e32 v23, v3
	v_lshlrev_b32_e32 v22, 1, v2
	v_lshl_add_u64 v[4:5], v[4:5], 0, v[22:23]
	s_waitcnt vmcnt(3)
	v_mov_b64_e32 v[4:5], v[100:101]
	v_mov_b64_e32 v[6:7], v[102:103]
	v_lshlrev_b32_e32 v2, 2, v2
	v_mov_b32_e32 v37, 0xe8a0000
	s_movk_i32 s0, 0x1000
	v_cmp_gt_u32_e64 s[0:1], s0, v17
	v_cndmask_b32_e32 v8, v80, v88, vcc
	v_cndmask_b32_e32 v9, v81, v89, vcc
	v_cndmask_b32_e32 v10, v82, v90, vcc
	v_cndmask_b32_e32 v11, v83, v91, vcc
	v_cndmask_b32_e32 v18, v84, v92, vcc
	v_cndmask_b32_e32 v19, v85, v93, vcc
	v_cndmask_b32_e32 v20, v86, v94, vcc
	v_cndmask_b32_e32 v21, v87, v95, vcc
	v_lshlrev_b32_e32 v24, 16, v4
	v_and_b32_e32 v25, 0xffff0000, v4
	v_lshlrev_b32_e32 v4, 16, v5
	v_and_b32_e32 v5, 0xffff0000, v5
	v_pk_mul_f32 v[28:29], v[24:25], v[24:25]
	v_pk_mul_f32 v[30:31], v[4:5], v[4:5]
	v_add_f32_e32 v28, v28, v29
	v_lshlrev_b32_e32 v26, 16, v6
	v_and_b32_e32 v27, 0xffff0000, v6
	v_add_f32_e32 v28, v28, v30
	v_pk_mul_f32 v[32:33], v[26:27], v[26:27]
	v_add_f32_e32 v28, v31, v28
	v_lshlrev_b32_e32 v6, 16, v7
	v_and_b32_e32 v7, 0xffff0000, v7
	v_add_f32_e32 v28, v32, v28
	v_pk_mul_f32 v[34:35], v[6:7], v[6:7]
	v_add_f32_e32 v28, v33, v28
	v_add_f32_e32 v28, v34, v28
	v_add_f32_e32 v28, v35, v28
	ds_bpermute_b32 v30, v12, v28
	v_mov_b32_e32 v29, v3
	v_mov_b32_e32 v31, v3
	v_mov_b32_e32 v33, v3
	v_lshlrev_b32_e32 v32, 7, v17
	s_mov_b64 s[98:99], vcc
	v_and_b32_e32 v120, 31, v17
	v_lshlrev_b32_e32 v120, 5, v120
	v_and_b32_e32 v121, 0xffffffe0, v17
	v_lshl_or_b32 v120, v121, 7, v120
	v_bfe_u32 v121, v15, 4, 2
	v_lshl_or_b32 v120, v121, 10, v120
	v_bfe_u32 v121, v15, 3, 1
	v_lshl_or_b32 v120, v121, 4, v120
	v_cndmask_b32_e64 v32, v32, v120, s[98:99]
	s_waitcnt lgkmcnt(0)
	v_add_f32_e32 v28, v28, v30
	ds_bpermute_b32 v34, v13, v28
	v_lshlrev_b32_e32 v30, 20, v16
	v_cndmask_b32_e64 v17, v232, 1.0, vcc
	s_waitcnt lgkmcnt(0)
	v_add_f32_e32 v34, v28, v34
	ds_bpermute_b32 v35, v14, v34
	v_mov_b32_e32 v28, 0xd8a0000
	v_cndmask_b32_e32 v28, v28, v37, vcc
	v_lshl_add_u64 v[28:29], s[28:29], 0, v[28:29]
	v_lshl_add_u64 v[28:29], v[28:29], 0, v[30:31]
	s_waitcnt lgkmcnt(0)
	v_add_f32_e32 v34, v34, v35
	v_fmamk_f32 v34, v34, 0x3c800000, v218
	v_mul_f32_e32 v35, 0x4b800000, v34
	v_cmp_gt_f32_e64 s[4:5], s71, v34
	v_lshl_add_u64 v[28:29], v[28:29], 0, v[32:33]
	v_cndmask_b32_e64 v22, v22, v3, s[98:99]
	v_lshl_add_u64 v[22:23], v[28:29], 0, v[22:23]
	v_cndmask_b32_e64 v34, v34, v35, s[4:5]
	v_rsq_f32_e32 v34, v34
	s_nop 0
	v_mul_f32_e32 v28, 0x45800000, v34
	v_cndmask_b32_e64 v28, v34, v28, s[4:5]
	v_mul_f32_e32 v28, v17, v28
	s_and_b64 s[4:5], vcc, s[0:1]
	v_pk_mul_f32 v[8:9], v[8:9], v[28:29] op_sel_hi:[1,0]
	v_pk_mul_f32 v[10:11], v[10:11], v[28:29] op_sel_hi:[1,0]
	v_pk_mul_f32 v[18:19], v[18:19], v[28:29] op_sel_hi:[1,0]
	v_pk_mul_f32 v[20:21], v[20:21], v[28:29] op_sel_hi:[1,0]
	v_pk_mul_f32 v[8:9], v[8:9], v[24:25]
	v_pk_mul_f32 v[10:11], v[10:11], v[4:5]
	v_pk_mul_f32 v[4:5], v[18:19], v[26:27]
	v_pk_mul_f32 v[6:7], v[20:21], v[6:7]
	v_cvt_pk_bf16_f32 v18, v8, v9
	v_cvt_pk_bf16_f32 v19, v10, v11
	v_cvt_pk_bf16_f32 v20, v4, v5
	v_cvt_pk_bf16_f32 v21, v6, v7
	global_store_dwordx4 v[22:23], v[18:21], off
	s_and_saveexec_b64 s[0:1], s[4:5]
	s_cbranch_execz .Lp0_t1
	v_lshrrev_b32_e32 v17, 7, v1
	v_lshrrev_b32_e32 v18, 11, v1
	v_and_or_b32 v16, v18, s16, v16
	v_lshlrev_b32_e32 v17, 8, v17
	v_perm_b32 v16, v16, v17, s17
	v_mov_b32_e32 v17, v3
	v_lshl_add_u64 v[16:17], s[8:9], 0, v[16:17]
	v_lshl_add_u64 v[16:17], v[16:17], 0, v[2:3]
	global_store_dwordx4 v[16:17], v[8:11], off
	global_store_dwordx4 v[16:17], v[4:7], off offset:16
.Lp0_t1:
	s_or_b64 exec, exec, s[0:1]
	v_add_u32_e32 v1, s2, v1
	v_add_u32_e32 v15, s3, v15
	v_ashrrev_i32_e32 v2, 10, v1
	v_bfe_u32 v17, v1, 7, 13
	v_mov_b64_e32 v[4:5], s[34:35]
	v_and_b32_e32 v6, 0xfffffc00, v2
	v_bfe_u32 v16, v1, 3, 4
	v_mad_u64_u32 v[4:5], s[0:1], v17, s67, v[4:5]
	v_ashrrev_i32_e32 v7, 31, v6
	v_lshl_add_u64 v[4:5], v[6:7], 1, v[4:5]
	v_lshlrev_b32_e32 v2, 7, v16
	v_lshl_add_u64 v[4:5], v[4:5], 0, v[2:3]
	v_cmp_lt_u32_e32 vcc, s15, v1
	v_and_b32_e32 v2, 56, v15
	v_mov_b32_e32 v23, v3
	v_lshlrev_b32_e32 v22, 1, v2
	v_lshl_add_u64 v[4:5], v[4:5], 0, v[22:23]
	s_waitcnt vmcnt(3)
	v_mov_b64_e32 v[4:5], v[104:105]
	v_mov_b64_e32 v[6:7], v[106:107]
	v_lshlrev_b32_e32 v2, 2, v2
	v_mov_b32_e32 v37, 0xe8a0000
	s_movk_i32 s0, 0x1000
	v_cmp_gt_u32_e64 s[0:1], s0, v17
	v_cndmask_b32_e32 v8, v80, v88, vcc
	v_cndmask_b32_e32 v9, v81, v89, vcc
	v_cndmask_b32_e32 v10, v82, v90, vcc
	v_cndmask_b32_e32 v11, v83, v91, vcc
	v_cndmask_b32_e32 v18, v84, v92, vcc
	v_cndmask_b32_e32 v19, v85, v93, vcc
	v_cndmask_b32_e32 v20, v86, v94, vcc
	v_cndmask_b32_e32 v21, v87, v95, vcc
	v_lshlrev_b32_e32 v24, 16, v4
	v_and_b32_e32 v25, 0xffff0000, v4
	v_lshlrev_b32_e32 v4, 16, v5
	v_and_b32_e32 v5, 0xffff0000, v5
	v_pk_mul_f32 v[28:29], v[24:25], v[24:25]
	v_pk_mul_f32 v[30:31], v[4:5], v[4:5]
	v_add_f32_e32 v28, v28, v29
	v_lshlrev_b32_e32 v26, 16, v6
	v_and_b32_e32 v27, 0xffff0000, v6
	v_add_f32_e32 v28, v28, v30
	v_pk_mul_f32 v[32:33], v[26:27], v[26:27]
	v_add_f32_e32 v28, v31, v28
	v_lshlrev_b32_e32 v6, 16, v7
	v_and_b32_e32 v7, 0xffff0000, v7
	v_add_f32_e32 v28, v32, v28
	v_pk_mul_f32 v[34:35], v[6:7], v[6:7]
	v_add_f32_e32 v28, v33, v28
	v_add_f32_e32 v28, v34, v28
	v_add_f32_e32 v28, v35, v28
	ds_bpermute_b32 v30, v12, v28
	v_mov_b32_e32 v29, v3
	v_mov_b32_e32 v31, v3
	v_mov_b32_e32 v33, v3
	v_lshlrev_b32_e32 v32, 7, v17
	s_mov_b64 s[98:99], vcc
	v_and_b32_e32 v120, 31, v17
	v_lshlrev_b32_e32 v120, 5, v120
	v_and_b32_e32 v121, 0xffffffe0, v17
	v_lshl_or_b32 v120, v121, 7, v120
	v_bfe_u32 v121, v15, 4, 2
	v_lshl_or_b32 v120, v121, 10, v120
	v_bfe_u32 v121, v15, 3, 1
	v_lshl_or_b32 v120, v121, 4, v120
	v_cndmask_b32_e64 v32, v32, v120, s[98:99]
	s_waitcnt lgkmcnt(0)
	v_add_f32_e32 v28, v28, v30
	ds_bpermute_b32 v34, v13, v28
	v_lshlrev_b32_e32 v30, 20, v16
	v_cndmask_b32_e64 v17, v232, 1.0, vcc
	s_waitcnt lgkmcnt(0)
	v_add_f32_e32 v34, v28, v34
	ds_bpermute_b32 v35, v14, v34
	v_mov_b32_e32 v28, 0xd8a0000
	v_cndmask_b32_e32 v28, v28, v37, vcc
	v_lshl_add_u64 v[28:29], s[28:29], 0, v[28:29]
	v_lshl_add_u64 v[28:29], v[28:29], 0, v[30:31]
	s_waitcnt lgkmcnt(0)
	v_add_f32_e32 v34, v34, v35
	v_fmamk_f32 v34, v34, 0x3c800000, v218
	v_mul_f32_e32 v35, 0x4b800000, v34
	v_cmp_gt_f32_e64 s[4:5], s71, v34
	v_lshl_add_u64 v[28:29], v[28:29], 0, v[32:33]
	v_cndmask_b32_e64 v22, v22, v3, s[98:99]
	v_lshl_add_u64 v[22:23], v[28:29], 0, v[22:23]
	v_cndmask_b32_e64 v34, v34, v35, s[4:5]
	v_rsq_f32_e32 v34, v34
	s_nop 0
	v_mul_f32_e32 v28, 0x45800000, v34
	v_cndmask_b32_e64 v28, v34, v28, s[4:5]
	v_mul_f32_e32 v28, v17, v28
	s_and_b64 s[4:5], vcc, s[0:1]
	v_pk_mul_f32 v[8:9], v[8:9], v[28:29] op_sel_hi:[1,0]
	v_pk_mul_f32 v[10:11], v[10:11], v[28:29] op_sel_hi:[1,0]
	v_pk_mul_f32 v[18:19], v[18:19], v[28:29] op_sel_hi:[1,0]
	v_pk_mul_f32 v[20:21], v[20:21], v[28:29] op_sel_hi:[1,0]
	v_pk_mul_f32 v[8:9], v[8:9], v[24:25]
	v_pk_mul_f32 v[10:11], v[10:11], v[4:5]
	v_pk_mul_f32 v[4:5], v[18:19], v[26:27]
	v_pk_mul_f32 v[6:7], v[20:21], v[6:7]
	v_cvt_pk_bf16_f32 v18, v8, v9
	v_cvt_pk_bf16_f32 v19, v10, v11
	v_cvt_pk_bf16_f32 v20, v4, v5
	v_cvt_pk_bf16_f32 v21, v6, v7
	global_store_dwordx4 v[22:23], v[18:21], off
	s_and_saveexec_b64 s[0:1], s[4:5]
	s_cbranch_execz .Lp0_t2
	v_lshrrev_b32_e32 v17, 7, v1
	v_lshrrev_b32_e32 v18, 11, v1
	v_and_or_b32 v16, v18, s16, v16
	v_lshlrev_b32_e32 v17, 8, v17
	v_perm_b32 v16, v16, v17, s17
	v_mov_b32_e32 v17, v3
	v_lshl_add_u64 v[16:17], s[8:9], 0, v[16:17]
	v_lshl_add_u64 v[16:17], v[16:17], 0, v[2:3]
	global_store_dwordx4 v[16:17], v[8:11], off
	global_store_dwordx4 v[16:17], v[4:7], off offset:16
.Lp0_t2:
	s_or_b64 exec, exec, s[0:1]
	v_add_u32_e32 v1, s2, v1
	v_add_u32_e32 v15, s3, v15
	v_ashrrev_i32_e32 v2, 10, v1
	v_bfe_u32 v17, v1, 7, 13
	v_mov_b64_e32 v[4:5], s[34:35]
	v_and_b32_e32 v6, 0xfffffc00, v2
	v_bfe_u32 v16, v1, 3, 4
	v_mad_u64_u32 v[4:5], s[0:1], v17, s67, v[4:5]
	v_ashrrev_i32_e32 v7, 31, v6
	v_lshl_add_u64 v[4:5], v[6:7], 1, v[4:5]
	v_lshlrev_b32_e32 v2, 7, v16
	v_lshl_add_u64 v[4:5], v[4:5], 0, v[2:3]
	v_cmp_lt_u32_e32 vcc, s15, v1
	v_and_b32_e32 v2, 56, v15
	v_mov_b32_e32 v23, v3
	v_lshlrev_b32_e32 v22, 1, v2
	v_lshl_add_u64 v[4:5], v[4:5], 0, v[22:23]
	s_waitcnt vmcnt(3)
	v_mov_b64_e32 v[4:5], v[108:109]
	v_mov_b64_e32 v[6:7], v[110:111]
	v_lshlrev_b32_e32 v2, 2, v2
	v_mov_b32_e32 v37, 0xe8a0000
	s_movk_i32 s0, 0x1000
	v_cmp_gt_u32_e64 s[0:1], s0, v17
	v_cndmask_b32_e32 v8, v80, v88, vcc
	v_cndmask_b32_e32 v9, v81, v89, vcc
	v_cndmask_b32_e32 v10, v82, v90, vcc
	v_cndmask_b32_e32 v11, v83, v91, vcc
	v_cndmask_b32_e32 v18, v84, v92, vcc
	v_cndmask_b32_e32 v19, v85, v93, vcc
	v_cndmask_b32_e32 v20, v86, v94, vcc
	v_cndmask_b32_e32 v21, v87, v95, vcc
	v_lshlrev_b32_e32 v24, 16, v4
	v_and_b32_e32 v25, 0xffff0000, v4
	v_lshlrev_b32_e32 v4, 16, v5
	v_and_b32_e32 v5, 0xffff0000, v5
	v_pk_mul_f32 v[28:29], v[24:25], v[24:25]
	v_pk_mul_f32 v[30:31], v[4:5], v[4:5]
	v_add_f32_e32 v28, v28, v29
	v_lshlrev_b32_e32 v26, 16, v6
	v_and_b32_e32 v27, 0xffff0000, v6
	v_add_f32_e32 v28, v28, v30
	v_pk_mul_f32 v[32:33], v[26:27], v[26:27]
	v_add_f32_e32 v28, v31, v28
	v_lshlrev_b32_e32 v6, 16, v7
	v_and_b32_e32 v7, 0xffff0000, v7
	v_add_f32_e32 v28, v32, v28
	v_pk_mul_f32 v[34:35], v[6:7], v[6:7]
	v_add_f32_e32 v28, v33, v28
	v_add_f32_e32 v28, v34, v28
	v_add_f32_e32 v28, v35, v28
	ds_bpermute_b32 v30, v12, v28
	v_mov_b32_e32 v29, v3
	v_mov_b32_e32 v31, v3
	v_mov_b32_e32 v33, v3
	v_lshlrev_b32_e32 v32, 7, v17
	s_mov_b64 s[98:99], vcc
	v_and_b32_e32 v120, 31, v17
	v_lshlrev_b32_e32 v120, 5, v120
	v_and_b32_e32 v121, 0xffffffe0, v17
	v_lshl_or_b32 v120, v121, 7, v120
	v_bfe_u32 v121, v15, 4, 2
	v_lshl_or_b32 v120, v121, 10, v120
	v_bfe_u32 v121, v15, 3, 1
	v_lshl_or_b32 v120, v121, 4, v120
	v_cndmask_b32_e64 v32, v32, v120, s[98:99]
	s_waitcnt lgkmcnt(0)
	v_add_f32_e32 v28, v28, v30
	ds_bpermute_b32 v34, v13, v28
	v_lshlrev_b32_e32 v30, 20, v16
	v_cndmask_b32_e64 v17, v232, 1.0, vcc
	s_waitcnt lgkmcnt(0)
	v_add_f32_e32 v34, v28, v34
	ds_bpermute_b32 v35, v14, v34
	v_mov_b32_e32 v28, 0xd8a0000
	v_cndmask_b32_e32 v28, v28, v37, vcc
	v_lshl_add_u64 v[28:29], s[28:29], 0, v[28:29]
	v_lshl_add_u64 v[28:29], v[28:29], 0, v[30:31]
	s_waitcnt lgkmcnt(0)
	v_add_f32_e32 v34, v34, v35
	v_fmamk_f32 v34, v34, 0x3c800000, v218
	v_mul_f32_e32 v35, 0x4b800000, v34
	v_cmp_gt_f32_e64 s[4:5], s71, v34
	v_lshl_add_u64 v[28:29], v[28:29], 0, v[32:33]
	v_cndmask_b32_e64 v22, v22, v3, s[98:99]
	v_lshl_add_u64 v[22:23], v[28:29], 0, v[22:23]
	v_cndmask_b32_e64 v34, v34, v35, s[4:5]
	v_rsq_f32_e32 v34, v34
	s_nop 0
	v_mul_f32_e32 v28, 0x45800000, v34
	v_cndmask_b32_e64 v28, v34, v28, s[4:5]
	v_mul_f32_e32 v28, v17, v28
	s_and_b64 s[4:5], vcc, s[0:1]
	v_pk_mul_f32 v[8:9], v[8:9], v[28:29] op_sel_hi:[1,0]
	v_pk_mul_f32 v[10:11], v[10:11], v[28:29] op_sel_hi:[1,0]
	v_pk_mul_f32 v[18:19], v[18:19], v[28:29] op_sel_hi:[1,0]
	v_pk_mul_f32 v[20:21], v[20:21], v[28:29] op_sel_hi:[1,0]
	v_pk_mul_f32 v[8:9], v[8:9], v[24:25]
	v_pk_mul_f32 v[10:11], v[10:11], v[4:5]
	v_pk_mul_f32 v[4:5], v[18:19], v[26:27]
	v_pk_mul_f32 v[6:7], v[20:21], v[6:7]
	v_cvt_pk_bf16_f32 v18, v8, v9
	v_cvt_pk_bf16_f32 v19, v10, v11
	v_cvt_pk_bf16_f32 v20, v4, v5
	v_cvt_pk_bf16_f32 v21, v6, v7
	global_store_dwordx4 v[22:23], v[18:21], off
	s_and_saveexec_b64 s[0:1], s[4:5]
	s_cbranch_execz .Lp0_t3
	v_lshrrev_b32_e32 v17, 7, v1
	v_lshrrev_b32_e32 v18, 11, v1
	v_and_or_b32 v16, v18, s16, v16
	v_lshlrev_b32_e32 v17, 8, v17
	v_perm_b32 v16, v16, v17, s17
	v_mov_b32_e32 v17, v3
	v_lshl_add_u64 v[16:17], s[8:9], 0, v[16:17]
	v_lshl_add_u64 v[16:17], v[16:17], 0, v[2:3]
	global_store_dwordx4 v[16:17], v[8:11], off
	global_store_dwordx4 v[16:17], v[4:7], off offset:16

.LBB0_771:
	v_ashrrev_i32_e32 v2, 10, v1
	v_bfe_u32 v17, v1, 7, 13
	v_mov_b64_e32 v[4:5], s[34:35]
	v_and_b32_e32 v6, 0xfffffc00, v2
	v_bfe_u32 v16, v1, 3, 4
	v_mad_u64_u32 v[4:5], s[0:1], v17, s67, v[4:5]
	v_ashrrev_i32_e32 v7, 31, v6
	v_lshl_add_u64 v[4:5], v[6:7], 1, v[4:5]
	v_lshlrev_b32_e32 v2, 7, v16
	v_lshl_add_u64 v[4:5], v[4:5], 0, v[2:3]
	v_cmp_lt_u32_e32 vcc, s15, v1
	v_mov_b32_e32 v2, 0xa8
	v_mov_b32_e32 v6, 0xb0
	v_cndmask_b32_e32 v2, v2, v6, vcc
	v_lshl_add_u64 v[6:7], s[30:31], 0, v[2:3]
	global_load_dwordx2 v[8:9], v[6:7], off
	v_and_b32_e32 v2, 56, v15
	v_mov_b32_e32 v23, v3
	v_lshlrev_b32_e32 v22, 1, v2
	v_lshl_add_u64 v[4:5], v[4:5], 0, v[22:23]
	global_load_dwordx4 v[4:7], v[4:5], off
	v_lshlrev_b32_e32 v2, 2, v2
	v_mov_b32_e32 v37, 0xe8a0000
	s_movk_i32 s0, 0x1000
	v_cmp_gt_u32_e64 s[0:1], s0, v17
	s_waitcnt vmcnt(0)
	v_lshl_add_u64 v[18:19], v[8:9], 0, v[2:3]
	global_load_dwordx4 v[8:11], v[18:19], off
	s_nop 0
	global_load_dwordx4 v[18:21], v[18:19], off offset:16
	v_lshlrev_b32_e32 v24, 16, v4
	v_and_b32_e32 v25, 0xffff0000, v4
	v_lshlrev_b32_e32 v4, 16, v5
	v_and_b32_e32 v5, 0xffff0000, v5
	v_pk_mul_f32 v[28:29], v[24:25], v[24:25]
	v_pk_mul_f32 v[30:31], v[4:5], v[4:5]
	v_add_f32_e32 v28, v28, v29
	v_lshlrev_b32_e32 v26, 16, v6
	v_and_b32_e32 v27, 0xffff0000, v6
	v_add_f32_e32 v28, v28, v30
	v_pk_mul_f32 v[32:33], v[26:27], v[26:27]
	v_add_f32_e32 v28, v31, v28
	v_lshlrev_b32_e32 v6, 16, v7
	v_and_b32_e32 v7, 0xffff0000, v7
	v_add_f32_e32 v28, v32, v28
	v_pk_mul_f32 v[34:35], v[6:7], v[6:7]
	v_add_f32_e32 v28, v33, v28
	v_add_f32_e32 v28, v34, v28
	v_add_f32_e32 v28, v35, v28
	ds_bpermute_b32 v30, v12, v28
	v_mov_b32_e32 v29, v3
	v_mov_b32_e32 v31, v3
	v_mov_b32_e32 v33, v3
	v_lshlrev_b32_e32 v32, 7, v17
	s_mov_b64 s[98:99], vcc
	v_and_b32_e32 v120, 31, v17
	v_lshlrev_b32_e32 v120, 5, v120
	v_and_b32_e32 v121, 0xffffffe0, v17
	v_lshl_or_b32 v120, v121, 7, v120
	v_bfe_u32 v121, v15, 4, 2
	v_lshl_or_b32 v120, v121, 10, v120
	v_bfe_u32 v121, v15, 3, 1
	v_lshl_or_b32 v120, v121, 4, v120
	v_cndmask_b32_e64 v32, v32, v120, s[98:99]
	s_waitcnt lgkmcnt(0)
	v_add_f32_e32 v28, v28, v30
	ds_bpermute_b32 v34, v13, v28
	v_lshlrev_b32_e32 v30, 20, v16
	v_cndmask_b32_e64 v17, v232, 1.0, vcc
	s_waitcnt lgkmcnt(0)
	v_add_f32_e32 v34, v28, v34
	ds_bpermute_b32 v35, v14, v34
	v_mov_b32_e32 v28, 0xd8a0000
	v_cndmask_b32_e32 v28, v28, v37, vcc
	v_lshl_add_u64 v[28:29], s[28:29], 0, v[28:29]
	v_lshl_add_u64 v[28:29], v[28:29], 0, v[30:31]
	s_waitcnt lgkmcnt(0)
	v_add_f32_e32 v34, v34, v35
	v_fmamk_f32 v34, v34, 0x3c800000, v218
	v_mul_f32_e32 v35, 0x4b800000, v34
	v_cmp_gt_f32_e64 s[4:5], s71, v34
	v_lshl_add_u64 v[28:29], v[28:29], 0, v[32:33]
	v_cndmask_b32_e64 v22, v22, v3, s[98:99]
	v_lshl_add_u64 v[22:23], v[28:29], 0, v[22:23]
	v_cndmask_b32_e64 v34, v34, v35, s[4:5]
	v_rsq_f32_e32 v34, v34
	s_nop 0
	v_mul_f32_e32 v28, 0x45800000, v34
	v_cndmask_b32_e64 v28, v34, v28, s[4:5]
	v_mul_f32_e32 v28, v17, v28
	s_and_b64 s[4:5], vcc, s[0:1]
	s_waitcnt vmcnt(1)
	v_pk_mul_f32 v[8:9], v[8:9], v[28:29] op_sel_hi:[1,0]
	v_pk_mul_f32 v[10:11], v[10:11], v[28:29] op_sel_hi:[1,0]
	s_waitcnt vmcnt(0)
	v_pk_mul_f32 v[18:19], v[18:19], v[28:29] op_sel_hi:[1,0]
	v_pk_mul_f32 v[20:21], v[20:21], v[28:29] op_sel_hi:[1,0]
	v_pk_mul_f32 v[8:9], v[8:9], v[24:25]
	v_pk_mul_f32 v[10:11], v[10:11], v[4:5]
	v_pk_mul_f32 v[4:5], v[18:19], v[26:27]
	v_pk_mul_f32 v[6:7], v[20:21], v[6:7]
	v_cvt_pk_bf16_f32 v18, v8, v9
	v_cvt_pk_bf16_f32 v19, v10, v11
	v_cvt_pk_bf16_f32 v20, v4, v5
	v_cvt_pk_bf16_f32 v21, v6, v7
	global_store_dwordx4 v[22:23], v[18:21], off
	s_and_saveexec_b64 s[0:1], s[4:5]
	s_cbranch_execz .LBB0_770
	v_lshrrev_b32_e32 v17, 7, v1
	v_lshrrev_b32_e32 v18, 11, v1
	v_and_or_b32 v16, v18, s16, v16
	v_lshlrev_b32_e32 v17, 8, v17
	v_perm_b32 v16, v16, v17, s17
	v_mov_b32_e32 v17, v3
	v_lshl_add_u64 v[16:17], s[8:9], 0, v[16:17]
	v_lshl_add_u64 v[16:17], v[16:17], 0, v[2:3]
	global_store_dwordx4 v[16:17], v[8:11], off
	global_store_dwordx4 v[16:17], v[4:7], off offset:16
	s_branch .LBB0_770
